# prompt attention items remapped so the 8 WGs of an XCD take 8 consecutive q-blocks of one (batch, kv head): shared K/V blocks hit the XCD-local L2
# speedup vs baseline: 1.0071x; 1.0024x over previous
.LBB0_541:
	s_or_b64 exec, exec, s[22:23]
	s_xor_b64 s[10:11], s[36:37], -1
	v_readlane_b32 s16, v254, 26
	v_writelane_b32 v255, s10, 55
	v_readlane_b32 s17, v254, 27
	s_mov_b64 s[12:13], s[0:1]
	v_writelane_b32 v255, s11, 56
	s_mov_b32 s10, s74
	s_and_b64 vcc, exec, s[16:17]
	s_waitcnt lgkmcnt(0)
	s_barrier
	s_cbranch_vccz .LBB0_779
	s_load_dwordx2 s[12:13], s[12:13], 0xd0
	s_lshl_b32 s16, s10, 6
	s_ashr_i32 s17, s16, 31
	s_lshl_b64 s[16:17], s[16:17], 2
	s_and_b32 s4, s2, 7
	s_lshr_b32 s11, s2, 3
	s_and_b32 s81, s11, 7
	s_lshr_b32 s11, s11, 3
	s_lshl_b32 s11, s11, 6
	s_lshl_b32 s81, s81, 1
	s_add_i32 s81, s81, s11
	s_lshr_b32 s11, s4, 1
	s_lshl_b32 s11, s11, 4
	s_add_i32 s81, s81, s11
	s_and_b32 s4, s4, 1
	s_add_i32 s81, s81, s4
	s_waitcnt lgkmcnt(0)
	s_add_u32 s4, s12, s16
	s_addc_u32 s11, s13, s17
	s_add_u32 s68, s4, 0xf031600
	s_addc_u32 s69, s11, 0
	s_lshl_b32 s84, s10, 8
	s_lshl_b32 s90, s10, 10
	s_lshl_b32 s75, s10, 7
	s_ashr_i32 s11, s10, 31
	s_lshl_b32 s58, s10, 3
	s_ashr_i32 s85, s84, 31
	s_ashr_i32 s91, s90, 31
	s_lshl_b32 s59, s10, 2
	s_lshl_b64 s[92:93], s[10:11], 15
	s_or_b32 s78, s75, 2
	s_or_b32 s79, s75, 3
	s_add_i32 s80, s75, 0xffffafc0
	s_branch .LBB0_545
